# stack18 + MA (EpiMix GEMM) next-unit scalar block also interleaved into its peeled first K-tile MFMAs
# speedup vs baseline: 1.0025x; 1.0012x over previous
; #define PG8_LDA(dst, b, h) do { _Pragma("unroll") for (int m = 0; m < 4; ++m) _Pragma("unroll") for (int k = 0; k < 2; ++k) dst[m][k] = *(const PG8_LAS bf16x8*)(lds + PG8_SA(b, h) + aoff + m * 2048 + k * 1024); } while (0)
;     __device__ __forceinline__ bool next(int i, Unit& u) const {
;         const long L = (long)i * G + c; if (L >= total) return false;
;         if (nM1 == 144 && nN1 == 8 && nM2 == 0 && G == 256) {
;             const int xcd = c & 7, o = c >> 3;
;             const int grp = (i < 4) ? xcd * 4 + i : 32 + (xcd >> 1), idx = (i < 4) ? o : (xcd & 1) * 16 + o;
;             u.pm = grp * 4 + (idx & 3); u.pn = idx >> 2; return true; }
;         int w = (int)L; { const int q = total / NXCD, r = total % NXCD, xcd = w % NXCD, off = w / NXCD; w = (xcd < r ? xcd * (q + 1) : r * (q + 1) + (xcd - r) * q) + off; }
;         int nM = nM1, nN = nN1; const bool second = w >= n1; if (second) { w -= n1; nM = nM2; nN = nN2; }
;         const int wgm = 4;
;         const int nig = wgm * nN, gid = w / nig, fm = gid * wgm, gsz = (nM - fm) < wgm ? (nM - fm) : wgm;
;         int pm = fm + ((w % nig) % gsz), pn = (w % nig) / gsz;
;         if (second) { pm += pm2; pn = pn < split ? a0 + pn : a1 + pn; }
;         u.pm = pm; u.pn = pn; return true;
; template <class Epi, class Sched, bool ALIGN_EPI = false, bool SP2 = false, bool ABLK = false, bool BBLK = false>
; __device__ __forceinline__ void gemm_phase(PG8_LAS unsigned char* lds, const Gemm g, const Sched& S, const Epi& E) {
;     ...
;         const char* nA = has_next ? (const char*)g.A + (size_t)nxt.pm * tstepA : cA; const char* nB = has_next ? (const char*)g.Bt + (size_t)nxt.pn * tstepB : cB;
;         for (int t = 0; t < nt; t += 2) {
;             const bool last = (t == nt - 2);
;             const char* a1 = cA + (size_t)(t + 1) * kstepA;
;             const char* a2 = last ? nA : cA + (size_t)(t + 2) * kstepA; const char* b2 = last ? nB : cB + (size_t)(t + 2) * kstepB;
;             const char* a3 = a2 + kstepA; const char* b3 = b2 + kstepB;
;             if (last && has_next) S.a_ready(nxt);
;             if constexpr (SP2) {
;             PG8_LDB(B0, 0, 0); PG8_LDB(B1, 0, 1); PG8_SCHED; PG8_LDA(At, 0, 0); PG8_STAGE(PG8_SA(1, 1), a1 + hstepA, voffA);
;             PG8_WAIT_V(8); PG8_WAIT_L(0); PG8_BAR; PG8_MMA(0, 0, At, B0); PG8_MMA(0, 1, At, B1); PG8_BAR; PG8_SCHED;
.LBB0_591:
	s_add_u32 s0, s0, 0xc000
	s_addc_u32 s1, s1, 0
	s_add_u32 s29, s30, 0x10000
	v_mov_b32_e32 v2, 0
	s_addc_u32 s40, s31, 0
	s_mov_b32 s41, -2
	v_mov_b32_e32 v3, v2
	v_mov_b32_e32 v4, v2
	v_mov_b32_e32 v5, v2
	v_mov_b32_e32 v6, v2
	v_mov_b32_e32 v7, v2
	v_mov_b32_e32 v8, v2
	v_mov_b32_e32 v9, v2
	s_waitcnt vmcnt(0)
	s_lshl_b32 s100, s8, 8
	s_add_i32 s100, s100, 0xfffff200
	s_cmp_gt_i32 s8, 13
	s_cselect_b32 s100, s100, 0
	s_ashr_i32 s101, s100, 31
	v_lshl_add_u64 v[250:251], s[100:101], 2, v[154:155]
	global_load_dwordx4 v[224:227], v[250:251], off
	global_load_dwordx4 v[246:249], v[250:251], off offset:16
	global_load_dwordx4 v[188:191], v[250:251], off offset:528
	s_nop 0
	global_load_dwordx4 v[250:253], v[250:251], off offset:512
	s_add_u32 s30, s0, 0x4000
	s_addc_u32 s31, s1, 0
	s_cmp_eq_u32 s41, 28
	s_cselect_b32 s36, s16, s30
	s_cselect_b32 s37, s9, s31
	s_cselect_b32 s34, s23, s29
	s_cselect_b32 s35, s21, s40
	s_add_u32 s30, s36, 0x8000
	s_addc_u32 s31, s37, 0
	s_add_i32 s60, 0, 0x10000
	s_add_i32 s75, 0, 0x14000
	v_add_u32_e32 v142, s60, v169
	v_add_u32_e32 v171, s75, v169
	ds_read_b128 v[130:133], v142
	ds_read_b128 v[134:137], v142 offset:1024
	ds_read_b128 v[138:141], v142 offset:2048
	ds_read_b128 v[142:145], v142 offset:3072
	ds_read_b128 v[160:163], v171
	ds_read_b128 v[164:167], v171 offset:1024
	ds_read_b128 v[172:175], v171 offset:2048
	ds_read_b128 v[176:179], v171 offset:3072
	v_lshl_add_u64 v[184:185], s[0:1], 0, v[156:157]
	s_add_i32 m0, s83, 0xc000
	ds_read_b128 v[180:183], v170
	ds_read_b128 v[196:199], v170 offset:1024
	ds_read_b128 v[200:203], v170 offset:2048
	ds_read_b128 v[204:207], v170 offset:3072
	ds_read_b128 v[208:211], v170 offset:4096
	ds_read_b128 v[212:215], v170 offset:5120
	ds_read_b128 v[216:219], v170 offset:6144
	ds_read_b128 v[220:223], v170 offset:7168
	global_load_lds_dwordx4 v[184:185], off
	v_lshl_add_u64 v[184:185], s[0:1], 0, v[158:159]
	s_add_i32 m0, s83, 0xe000
	s_nop 0
	global_load_lds_dwordx4 v[184:185], off
	s_waitcnt vmcnt(8)
	s_waitcnt lgkmcnt(0)
	s_barrier
	s_setprio 1
	s_waitcnt lgkmcnt(0)
	v_mfma_f32_16x16x32_bf16 v[126:129], v[130:133], v[180:183], 0
	s_add_i32 s93, s93, 1
	s_mul_i32 s6, s93, s56
	v_mfma_f32_16x16x32_bf16 v[122:125], v[138:141], v[180:183], 0
	s_mul_hi_u32 s7, s93, s42
	s_add_i32 s7, s7, s6
	v_mfma_f32_16x16x32_bf16 v[110:113], v[130:133], v[200:203], 0
	s_mul_i32 s6, s93, s42
	s_add_u32 s24, s6, s46
	v_mfma_f32_16x16x32_bf16 v[106:109], v[138:141], v[200:203], 0
	s_addc_u32 s25, s7, s68
	v_mov_b64_e32 v[228:229], s[2:3]
	v_mfma_f32_16x16x32_bf16 v[94:97], v[130:133], v[208:211], 0
	v_cmp_lt_i64_e64 s[6:7], s[24:25], v[228:229]
	s_ashr_i32 s9, s24, 31
	v_mfma_f32_16x16x32_bf16 v[90:93], v[138:141], v[208:211], 0
	s_lshr_b32 s9, s9, 29
	s_add_i32 s9, s24, s9
	v_mfma_f32_16x16x32_bf16 v[78:81], v[130:133], v[216:219], 0
	s_ashr_i32 s16, s9, 3
	s_and_b32 s9, s9, -8
	v_mfma_f32_16x16x32_bf16 v[74:77], v[138:141], v[216:219], 0
	s_sub_i32 s9, s24, s9
	s_lshr_b32 s20, s9, 31
	v_mfma_f32_16x16x32_bf16 v[126:129], v[134:137], v[196:199], v[126:129]
	s_or_b32 s20, s72, s20
	s_mul_i32 s9, s20, s9
	v_mfma_f32_16x16x32_bf16 v[122:125], v[142:145], v[196:199], v[122:125]
	s_add_i32 s9, s9, s16
	s_cmpk_lt_i32 s9, 0x1300
	v_mfma_f32_16x16x32_bf16 v[110:113], v[134:137], v[204:207], v[110:113]
	s_cselect_b32 s21, 0x98, s73
	s_cselect_b32 s16, 0, 0xffffed00
	v_mfma_f32_16x16x32_bf16 v[106:109], v[142:145], v[204:207], v[106:109]
	s_cselect_b32 s20, 0x80, 16
	s_abs_i32 s22, s21
	v_mfma_f32_16x16x32_bf16 v[94:97], v[134:137], v[212:215], v[94:97]
	v_cvt_f32_u32_e32 v228, s22
	s_sub_i32 s25, 0, s22
	v_mfma_f32_16x16x32_bf16 v[90:93], v[142:145], v[212:215], v[90:93]
	s_add_i32 s16, s16, s9
	s_abs_i32 s24, s16
	v_mfma_f32_16x16x32_bf16 v[78:81], v[134:137], v[220:223], v[78:81]
	v_rcp_iflag_f32_e32 v228, v228
	s_xor_b32 s23, s16, s21
	v_mfma_f32_16x16x32_bf16 v[74:77], v[142:145], v[220:223], v[74:77]
	s_ashr_i32 s23, s23, 31
	v_mul_f32_e32 v228, 0x4f7ffffe, v228
	s_setprio 0
	s_setprio 1
	v_mfma_f32_16x16x32_bf16 v[118:121], v[160:163], v[180:183], 0
	v_cvt_u32_f32_e32 v228, v228
	s_nop 0
	v_mfma_f32_16x16x32_bf16 v[114:117], v[172:175], v[180:183], 0
	v_readfirstlane_b32 s26, v228
	s_mul_i32 s25, s25, s26
	v_mfma_f32_16x16x32_bf16 v[102:105], v[160:163], v[200:203], 0
	s_mul_hi_u32 s25, s26, s25
	s_add_i32 s26, s26, s25
	v_mfma_f32_16x16x32_bf16 v[98:101], v[172:175], v[200:203], 0
	s_mul_hi_u32 s25, s24, s26
	s_mul_i32 s26, s25, s22
	v_mfma_f32_16x16x32_bf16 v[86:89], v[160:163], v[208:211], 0
	s_sub_i32 s24, s24, s26
	s_add_i32 s27, s25, 1
	v_mfma_f32_16x16x32_bf16 v[82:85], v[172:175], v[208:211], 0
	s_sub_i32 s26, s24, s22
	s_cmp_ge_u32 s24, s22
	v_mfma_f32_16x16x32_bf16 v[70:73], v[160:163], v[216:219], 0
	s_cselect_b32 s25, s27, s25
	s_cselect_b32 s24, s26, s24
	v_mfma_f32_16x16x32_bf16 v[66:69], v[172:175], v[216:219], 0
	s_add_i32 s26, s25, 1
	s_cmp_ge_u32 s24, s22
	v_mfma_f32_16x16x32_bf16 v[118:121], v[164:167], v[196:199], v[118:121]
	s_cselect_b32 s22, s26, s25
	s_xor_b32 s22, s22, s23
	v_mfma_f32_16x16x32_bf16 v[114:117], v[176:179], v[196:199], v[114:117]
	s_sub_i32 s22, s22, s23
	s_lshl_b32 s23, s22, 2
	v_mfma_f32_16x16x32_bf16 v[102:105], v[164:167], v[204:207], v[102:105]
	s_sub_i32 s20, s20, s23
	s_min_i32 s20, s20, 4
	v_mfma_f32_16x16x32_bf16 v[98:101], v[176:179], v[204:207], v[98:101]
	s_abs_i32 s24, s20
	v_cvt_f32_u32_e32 v228, s24
	v_mfma_f32_16x16x32_bf16 v[86:89], v[164:167], v[212:215], v[86:89]
	s_sub_i32 s25, 0, s24
	s_mul_i32 s22, s22, s21
	v_mfma_f32_16x16x32_bf16 v[82:85], v[176:179], v[212:215], v[82:85]
	s_sub_i32 s16, s16, s22
	v_rcp_iflag_f32_e32 v228, v228
	v_mfma_f32_16x16x32_bf16 v[70:73], v[164:167], v[220:223], v[70:73]
	s_abs_i32 s21, s16
	s_xor_b32 s22, s16, s20
	v_mfma_f32_16x16x32_bf16 v[66:69], v[176:179], v[220:223], v[66:69]
	s_ashr_i32 s22, s22, 31
	v_mul_f32_e32 v228, 0x4f7ffffe, v228
	s_setprio 0
	s_barrier
; #define PG8_STAGE(bufoff, gbase, voff) do { _Pragma("unroll") for (int _i = 0; _i < 2; ++_i) \
;         __builtin_amdgcn_global_load_lds((const unsigned*)((const char*)(gbase) + (voff)[_i]), (PG8_LAS unsigned*)(lds + (bufoff) + ldsw + _i * 8192), 16, 0, 0); } while (0)
; #define PG8_LDA(dst, b, h) do { _Pragma("unroll") for (int m = 0; m < 4; ++m) _Pragma("unroll") for (int k = 0; k < 2; ++k) dst[m][k] = *(const PG8_LAS bf16x8*)(lds + PG8_SA(b, h) + aoff + m * 2048 + k * 1024); } while (0)
; #define PG8_WAIT_V(n) asm volatile("s_waitcnt vmcnt(" #n ")" ::: "memory")
; #define PG8_WAIT_L(n) asm volatile("s_waitcnt lgkmcnt(" #n ")" ::: "memory")
; #define PG8_BAR __builtin_amdgcn_s_barrier()
; #define PG8_SCHED __builtin_amdgcn_sched_barrier(0)
;     __device__ __forceinline__ bool next(int i, Unit& u) const {
;         const long L = (long)i * G + c; if (L >= total) return false;
;         if (nM1 == 144 && nN1 == 8 && nM2 == 0 && G == 256) {
;             const int xcd = c & 7, o = c >> 3;
;             const int grp = (i < 4) ? xcd * 4 + i : 32 + (xcd >> 1), idx = (i < 4) ? o : (xcd & 1) * 16 + o;
;             u.pm = grp * 4 + (idx & 3); u.pn = idx >> 2; return true; }
;         int w = (int)L; { const int q = total / NXCD, r = total % NXCD, xcd = w % NXCD, off = w / NXCD; w = (xcd < r ? xcd * (q + 1) : r * (q + 1) + (xcd - r) * q) + off; }
;         int nM = nM1, nN = nN1; const bool second = w >= n1; if (second) { w -= n1; nM = nM2; nN = nN2; }
;         const int wgm = 4;
;         const int nig = wgm * nN, gid = w / nig, fm = gid * wgm, gsz = (nM - fm) < wgm ? (nM - fm) : wgm;
;         int pm = fm + ((w % nig) % gsz), pn = (w % nig) / gsz;
;         if (second) { pm += pm2; pn = pn < split ? a0 + pn : a1 + pn; }
;         u.pm = pm; u.pn = pn; return true;
; template <class Epi, class Sched, bool ALIGN_EPI = false, bool SP2 = false, bool ABLK = false, bool BBLK = false>
; __device__ __forceinline__ void gemm_phase(PG8_LAS unsigned char* lds, const Gemm g, const Sched& S, const Epi& E) {
;     ...
;             PG8_LDA(At, 0, 1); PG8_STAGE(PG8_SB(0, 0), b2, voffB); PG8_STAGE(PG8_SB(0, 1), b2 + hstepB, voffB); PG8_STAGE(PG8_SA(0, 0), a2, voffA);
;             PG8_WAIT_V(8); PG8_WAIT_L(0); PG8_BAR; PG8_MMA(1, 0, At, B0); PG8_MMA(1, 1, At, B1); PG8_BAR; PG8_SCHED;
	s_add_i32 s60, s60, s81
	v_lshl_add_u64 v[184:185], s[34:35], 0, v[148:149]
	s_mov_b32 m0, s60
	ds_read_b128 v[180:183], v170 offset:16384
	ds_read_b128 v[196:199], v170 offset:17408
	ds_read_b128 v[200:203], v170 offset:18432
	ds_read_b128 v[204:207], v170 offset:19456
	ds_read_b128 v[208:211], v170 offset:20480
	ds_read_b128 v[212:215], v170 offset:21504
	ds_read_b128 v[216:219], v170 offset:22528
	ds_read_b128 v[220:223], v170 offset:23552
	global_load_lds_dwordx4 v[184:185], off
	s_add_i32 m0, s60, 0x2000
	s_add_u32 s60, s34, 0x4000
	v_lshl_add_u64 v[184:185], s[34:35], 0, v[152:153]
	s_addc_u32 s61, s35, 0
	s_add_i32 s75, s75, s81
	global_load_lds_dwordx4 v[184:185], off
	v_lshl_add_u64 v[184:185], s[60:61], 0, v[148:149]
	s_mov_b32 m0, s75
	s_nop 0
	global_load_lds_dwordx4 v[184:185], off
	v_lshl_add_u64 v[184:185], s[60:61], 0, v[152:153]
	s_add_i32 m0, s75, 0x2000
	s_nop 0
	global_load_lds_dwordx4 v[184:185], off
	v_lshl_add_u64 v[184:185], s[36:37], 0, v[146:147]
	s_mov_b32 m0, s83
	s_nop 0
	global_load_lds_dwordx4 v[184:185], off
	v_lshl_add_u64 v[184:185], s[36:37], 0, v[150:151]
	s_mov_b32 m0, s84
	s_nop 0
	global_load_lds_dwordx4 v[184:185], off
	s_waitcnt vmcnt(8)
	s_waitcnt lgkmcnt(0)
	s_barrier
	s_setprio 1
	s_waitcnt lgkmcnt(0)
	v_mfma_f32_16x16x32_bf16 v[62:65], v[130:133], v[180:183], 0
	v_cvt_u32_f32_e32 v228, v228
	s_nop 0
	v_mfma_f32_16x16x32_bf16 v[58:61], v[138:141], v[180:183], 0
	v_readfirstlane_b32 s26, v228
	s_mul_i32 s25, s25, s26
	v_mfma_f32_16x16x32_bf16 v[46:49], v[130:133], v[200:203], 0
	s_mul_hi_u32 s25, s26, s25
	s_add_i32 s26, s26, s25
	v_mfma_f32_16x16x32_bf16 v[42:45], v[138:141], v[200:203], 0
	s_mul_hi_u32 s25, s21, s26
	s_mul_i32 s26, s25, s24
	v_mfma_f32_16x16x32_bf16 v[30:33], v[130:133], v[208:211], 0
	s_sub_i32 s21, s21, s26
	s_add_i32 s27, s25, 1
	v_mfma_f32_16x16x32_bf16 v[26:29], v[138:141], v[208:211], 0
	s_sub_i32 s26, s21, s24
	s_cmp_ge_u32 s21, s24
	v_mfma_f32_16x16x32_bf16 v[14:17], v[130:133], v[216:219], 0
	s_cselect_b32 s25, s27, s25
	s_cselect_b32 s21, s26, s21
	v_mfma_f32_16x16x32_bf16 v[10:13], v[138:141], v[216:219], 0
	s_add_i32 s26, s25, 1
	s_cmp_ge_u32 s21, s24
	v_mfma_f32_16x16x32_bf16 v[62:65], v[134:137], v[196:199], v[62:65]
	s_cselect_b32 s21, s26, s25
	s_xor_b32 s21, s21, s22
	v_mfma_f32_16x16x32_bf16 v[58:61], v[142:145], v[196:199], v[58:61]
	s_sub_i32 s21, s21, s22
	s_mul_i32 s20, s21, s20
	v_mfma_f32_16x16x32_bf16 v[46:49], v[134:137], v[204:207], v[46:49]
	s_sub_i32 s16, s16, s20
	s_add_i32 s16, s16, s23
	v_mfma_f32_16x16x32_bf16 v[42:45], v[142:145], v[204:207], v[42:45]
	s_add_i32 s20, s16, 0x80
	s_cmpk_lt_i32 s9, 0x1300
	v_mfma_f32_16x16x32_bf16 v[30:33], v[134:137], v[212:215], v[30:33]
	s_cselect_b32 s20, s16, s20
	s_cmp_lt_i32 s21, s33
	v_mfma_f32_16x16x32_bf16 v[26:29], v[142:145], v[212:215], v[26:29]
	s_cselect_b32 s16, s47, s65
	s_cmpk_lt_i32 s9, 0x1300
	v_mfma_f32_16x16x32_bf16 v[14:17], v[134:137], v[220:223], v[14:17]
	s_cselect_b32 s9, 0, s16
	s_add_i32 s22, s9, s21
	v_mfma_f32_16x16x32_bf16 v[10:13], v[142:145], v[220:223], v[10:13]
	s_ashr_i32 s21, s20, 31
	s_lshl_b64 s[24:25], s[20:21], 20
	s_setprio 0
	s_setprio 1
	v_mfma_f32_16x16x32_bf16 v[54:57], v[160:163], v[180:183], 0
	s_add_u32 s24, s51, s24
	s_addc_u32 s25, s53, s25
	v_mfma_f32_16x16x32_bf16 v[50:53], v[172:175], v[180:183], 0
	s_and_b64 s[26:27], s[6:7], exec
	s_cselect_b32 s9, s25, s1
	v_mfma_f32_16x16x32_bf16 v[38:41], v[160:163], v[200:203], 0
	s_cselect_b32 s16, s24, s0
	s_ashr_i32 s23, s22, 31
	v_mfma_f32_16x16x32_bf16 v[34:37], v[172:175], v[200:203], 0
	s_lshl_b64 s[26:27], s[22:23], 20
	s_add_u32 s26, s44, s26
	v_mfma_f32_16x16x32_bf16 v[22:25], v[160:163], v[208:211], 0
	s_addc_u32 s27, s45, s27
	s_and_b64 s[100:101], s[6:7], exec
	v_mfma_f32_16x16x32_bf16 v[18:21], v[172:175], v[208:211], 0
	s_cselect_b32 s21, s27, s31
	s_cselect_b32 s23, s26, s30
	v_mfma_f32_16x16x32_bf16 v[6:9], v[160:163], v[216:219], 0
	v_mfma_f32_16x16x32_bf16 v[2:5], v[172:175], v[216:219], 0
	v_mfma_f32_16x16x32_bf16 v[54:57], v[164:167], v[196:199], v[54:57]
	v_mfma_f32_16x16x32_bf16 v[50:53], v[176:179], v[196:199], v[50:53]
	v_mfma_f32_16x16x32_bf16 v[38:41], v[164:167], v[204:207], v[38:41]
	v_mfma_f32_16x16x32_bf16 v[34:37], v[176:179], v[204:207], v[34:37]
	v_mfma_f32_16x16x32_bf16 v[22:25], v[164:167], v[212:215], v[22:25]
	v_mfma_f32_16x16x32_bf16 v[18:21], v[176:179], v[212:215], v[18:21]
	v_mfma_f32_16x16x32_bf16 v[6:9], v[164:167], v[220:223], v[6:9]
	v_mfma_f32_16x16x32_bf16 v[2:5], v[176:179], v[220:223], v[2:5]
	s_setprio 0
	s_barrier
	s_branch .Lmid_594
